# MLA loop trims: tile-0 key mask moved to a rarely taken branch (24 v_cndmask per 2 tiles -> 12 v_mov), one s_waitcnt per QK MFMA pair instead of two, dead vmcnt ladders removed
# speedup vs baseline: 1.0047x; 1.0047x over previous
; #define QSTEP(d, A, B, NA, NB) do { if ((d) + 2 < 12) { NA = KLD((d) + 2, 0); NB = KLD((d) + 2, 1); } SBAR(); \
;     p0 = __builtin_amdgcn_mfma_f32_32x32x16_bf16(A, qr[d], p0, 0, 0, 0); p1 = __builtin_amdgcn_mfma_f32_32x32x16_bf16(B, qr[d], p1, 0, 0, 0); SBAR(); } while (0)
; __device__ __forceinline__ void partialSM(f32x16& p0, f32x16& p1, float& m_reg, float& mn, float& alpha) {
;   constexpr float C = SCALE * 1.4426950408889634f;
;   float pmax = p0[0];
; #pragma unroll
;   for (int r = 1; r < 16; ++r) pmax = fmaxf(pmax, p0[r]);
; #pragma unroll
;   for (int r = 0; r < 16; ++r) pmax = fmaxf(pmax, p1[r]);
;   { auto rr = __builtin_amdgcn_permlane32_swap(__float_as_uint(pmax), __float_as_uint(pmax), false, false);
;     pmax = fmaxf(__uint_as_float(rr[0]), __uint_as_float(rr[1])); }
; __device__ __forceinline__ void qkt2(f32x16& p0, f32x16& p1, const char* Ks, const bf16x8* qr, const int* kb4) {
;     ...
;   p0 = f32x16{}; p1 = f32x16{};
;   bf16x8 a0 = KLD(0, 0), b0 = KLD(0, 1), a1 = KLD(1, 0), b1 = KLD(1, 1), a2, b2;
;     ...
;   QSTEP(0, a0, b0, a2, b2); QSTEP(1, a1, b1, a0, b0); QSTEP(2, a2, b2, a1, b1);
;   QSTEP(3, a0, b0, a2, b2); QSTEP(4, a1, b1, a0, b0); QSTEP(5, a2, b2, a1, b1);
;   QSTEP(6, a0, b0, a2, b2); QSTEP(7, a1, b1, a0, b0); QSTEP(8, a2, b2, a1, b1);
;   QSTEP(9, a0, b0, a2, b2); QSTEP(10, a1, b1, a0, b0); QSTEP(11, a2, b2, a1, b1);
.LBB0_441:
	ds_read_b128 v[64:67], v210 offset:32768
	ds_read_b128 v[80:83], v210 offset:45056
	ds_read_b128 v[222:225], v209 offset:32768
	ds_read_b128 v[226:229], v209 offset:45056
	ds_read_b128 v[230:233], v208 offset:32768
	ds_read_b128 v[234:237], v208 offset:45056
	s_waitcnt vmcnt(0)
	v_lshl_add_u64 v[196:197], s[52:53], 0, v[192:193]
	v_add_co_u32_e32 v144, vcc, s28, v196
	v_lshl_add_u64 v[194:195], s[52:53], 0, v[190:191]
	s_nop 0
	v_addc_co_u32_e32 v145, vcc, 0, v197, vcc
	v_add_co_u32_e32 v146, vcc, s29, v194
	s_nop 1
	v_addc_co_u32_e32 v147, vcc, 0, v195, vcc
	s_waitcnt lgkmcnt(4)
	v_mfma_f32_32x32x16_bf16 v[64:79], v[64:67], v[96:99], 0
	v_mfma_f32_32x32x16_bf16 v[80:95], v[80:83], v[96:99], 0
	ds_write_b128 v212, v[164:167] offset:16384
	ds_write_b128 v212, v[168:171] offset:17408
	ds_read_b128 v[238:241], v207 offset:32768
	ds_read_b128 v[242:245], v207 offset:45056
	s_waitcnt lgkmcnt(6)
	v_mfma_f32_32x32x16_bf16 v[64:79], v[222:225], v[100:103], v[64:79]
	v_mfma_f32_32x32x16_bf16 v[80:95], v[226:229], v[100:103], v[80:95]
	ds_write_b128 v211, v[172:175] offset:57344
	ds_write_b128 v211, v[176:179] offset:57472
	ds_read_b128 v[222:225], v210 offset:32896
	ds_read_b128 v[226:229], v210 offset:45184
	global_load_dwordx4 v[164:167], v[144:145], off offset:256
	global_load_dwordx4 v[168:171], v[144:145], off offset:384
	s_waitcnt lgkmcnt(8)
	v_mfma_f32_32x32x16_bf16 v[64:79], v[230:233], v[104:107], v[64:79]
	v_mfma_f32_32x32x16_bf16 v[80:95], v[234:237], v[104:107], v[80:95]
	ds_write_b128 v211, v[180:183] offset:57600
	ds_read_b128 v[230:233], v209 offset:32896
	ds_read_b128 v[234:237], v209 offset:45184
	global_load_dwordx4 v[172:175], v[146:147], off
	global_load_dwordx4 v[176:179], v[146:147], off offset:128
	s_waitcnt lgkmcnt(7)
	v_mfma_f32_32x32x16_bf16 v[64:79], v[238:241], v[108:111], v[64:79]
	v_mfma_f32_32x32x16_bf16 v[80:95], v[242:245], v[108:111], v[80:95]
	ds_read_b128 v[238:241], v208 offset:32896
	ds_read_b128 v[242:245], v208 offset:45184
	global_load_dwordx4 v[180:183], v[146:147], off offset:256
	s_waitcnt lgkmcnt(5)
	v_mfma_f32_32x32x16_bf16 v[64:79], v[222:225], v[112:115], v[64:79]
	v_mfma_f32_32x32x16_bf16 v[80:95], v[226:229], v[112:115], v[80:95]
	ds_read_b128 v[222:225], v207 offset:32896
	ds_read_b128 v[226:229], v207 offset:45184
	s_waitcnt lgkmcnt(4)
	v_mfma_f32_32x32x16_bf16 v[64:79], v[230:233], v[116:119], v[64:79]
	v_mfma_f32_32x32x16_bf16 v[80:95], v[234:237], v[116:119], v[80:95]
	ds_read_b128 v[230:233], v210 offset:33024
	ds_read_b128 v[234:237], v210 offset:45312
	s_waitcnt lgkmcnt(4)
	v_mfma_f32_32x32x16_bf16 v[64:79], v[238:241], v[120:123], v[64:79]
	v_mfma_f32_32x32x16_bf16 v[80:95], v[242:245], v[120:123], v[80:95]
	ds_read_b128 v[238:241], v209 offset:33024
	ds_read_b128 v[242:245], v209 offset:45312
	s_waitcnt lgkmcnt(4)
	v_mfma_f32_32x32x16_bf16 v[64:79], v[222:225], v[124:127], v[64:79]
	v_mfma_f32_32x32x16_bf16 v[80:95], v[226:229], v[124:127], v[80:95]
	ds_read_b128 v[222:225], v208 offset:33024
	ds_read_b128 v[226:229], v208 offset:45312
	s_waitcnt lgkmcnt(4)
	v_mfma_f32_32x32x16_bf16 v[64:79], v[230:233], v[132:135], v[64:79]
	v_mfma_f32_32x32x16_bf16 v[80:95], v[234:237], v[132:135], v[80:95]
	ds_read_b128 v[230:233], v207 offset:33024
	ds_read_b128 v[234:237], v207 offset:45312
	s_waitcnt lgkmcnt(4)
	v_mfma_f32_32x32x16_bf16 v[64:79], v[238:241], v[140:143], v[64:79]
	v_mfma_f32_32x32x16_bf16 v[80:95], v[242:245], v[140:143], v[80:95]
	s_waitcnt lgkmcnt(2)
	v_mfma_f32_32x32x16_bf16 v[64:79], v[222:225], v[128:131], v[64:79]
	v_mfma_f32_32x32x16_bf16 v[80:95], v[226:229], v[128:131], v[80:95]
	s_waitcnt lgkmcnt(0)
	v_mfma_f32_32x32x16_bf16 v[64:79], v[230:233], v[136:139], v[64:79]
	v_mfma_f32_32x32x16_bf16 v[80:95], v[234:237], v[136:139], v[80:95]
	s_cmp_eq_u32 s42, 0
	s_cbranch_scc1 .Lmask0_b
	s_nop 7
	v_mov_b32_e32 v222, v76
	v_mov_b32_e32 v223, v77
	v_mov_b32_e32 v76, v90
	v_mov_b32_e32 v77, v91
	v_max_f32_e32 v90, v65, v65
	v_max_f32_e32 v91, v64, v64
	v_max_f32_e32 v90, v91, v90
	v_max3_f32 v90, v90, v66, v67
	v_max3_f32 v90, v90, v68, v69
	v_mov_b32_e32 v226, v72
	v_mov_b32_e32 v227, v73
	v_max3_f32 v90, v90, v70, v71
	v_mov_b32_e32 v224, v74
	v_mov_b32_e32 v225, v75
	v_max3_f32 v90, v90, v226, v227
	v_max3_f32 v90, v90, v224, v225
	v_max3_f32 v90, v90, v222, v223
	v_max3_f32 v90, v90, v78, v79
	v_max3_f32 v90, v90, v80, v81
	v_max3_f32 v90, v90, v82, v83
	v_max3_f32 v90, v90, v84, v85
	v_max3_f32 v90, v90, v86, v87
	v_max3_f32 v90, v90, v88, v89
	v_mov_b32_e32 v74, v92
	v_mov_b32_e32 v75, v93
	v_max3_f32 v90, v90, v76, v77
	v_mov_b32_e32 v73, v94
	v_mov_b32_e32 v72, v95
	v_max3_f32 v90, v90, v74, v75
	v_max3_f32 v90, v90, v73, v72
; __device__ __forceinline__ void partialSM(f32x16& p0, f32x16& p1, float& m_reg, float& mn, float& alpha) {
;     ...
;   { auto rr = __builtin_amdgcn_permlane32_swap(__float_as_uint(pmax), __float_as_uint(pmax), false, false);
;     pmax = fmaxf(__uint_as_float(rr[0]), __uint_as_float(rr[1])); }
;   if (__builtin_expect(__all(pmax - m_reg <= THR / SCALE), 1)) { mn = m_reg; alpha = 1.f; }
;   else { mn = fmaxf(m_reg, pmax); alpha = __builtin_amdgcn_exp2f((m_reg - mn) * C); m_reg = mn; }
.Lback0_b:
	v_mov_b32_e32 v91, v90
	s_nop 1
	v_permlane32_swap_b32_e32 v90, v91
	v_max_f32_e32 v91, v91, v91
	v_max_f32_e32 v90, v90, v90
	v_max_f32_e32 v90, v90, v91
	v_max_f32_e32 v92, v220, v220
	v_sub_f32_e32 v91, v90, v220
	v_max_f32_e32 v90, v92, v90
	v_sub_f32_e32 v92, v220, v90
	v_mul_f32_e32 v92, 0x3dd53b94, v92
	v_exp_f32_e32 v92, v92
	v_cmp_ge_f32_e32 vcc, s30, v91
	s_cmp_eq_u64 vcc, exec
	s_cselect_b64 s[8:9], -1, 0
	s_waitcnt lgkmcnt(0)
	s_barrier
	v_cndmask_b32_e64 v221, v92, 1.0, s[8:9]
	v_cmp_gt_f32_e32 vcc, 1.0, v221
	s_cbranch_vccz .LBB0_445
	s_and_saveexec_b64 s[0:1], s[6:7]
	ds_write_b32 v205, v221 offset:128
	s_or_b64 exec, exec, s[0:1]
	s_waitcnt lgkmcnt(0)
	v_add_u32_e32 v91, s3, v184
	ds_read_b128 v[92:95], v91 offset:224
	ds_read_b128 v[228:231], v91 offset:192
	ds_read_b128 v[232:235], v91 offset:160
	ds_read_b128 v[236:239], v91 offset:128
	s_waitcnt lgkmcnt(3)
	v_pk_mul_f32 v[12:13], v[12:13], v[92:93]
	s_waitcnt lgkmcnt(2)
	v_pk_mul_f32 v[8:9], v[8:9], v[228:229]
	s_waitcnt lgkmcnt(1)
	v_pk_mul_f32 v[4:5], v[4:5], v[232:233]
	v_pk_mul_f32 v[14:15], v[14:15], v[94:95]
	v_pk_mul_f32 v[10:11], v[10:11], v[230:231]
	v_pk_mul_f32 v[6:7], v[6:7], v[234:235]
	s_waitcnt lgkmcnt(0)
	v_pk_mul_f32 v[2:3], v[2:3], v[238:239]
	v_pk_mul_f32 v[0:1], v[0:1], v[236:237]
	v_pk_mul_f32 v[60:61], v[60:61], v[92:93]
	v_pk_mul_f32 v[56:57], v[56:57], v[228:229]
	v_pk_mul_f32 v[52:53], v[52:53], v[232:233]
	v_pk_mul_f32 v[62:63], v[62:63], v[94:95]
	v_pk_mul_f32 v[58:59], v[58:59], v[230:231]
	v_pk_mul_f32 v[54:55], v[54:55], v[234:235]
	v_pk_mul_f32 v[50:51], v[50:51], v[238:239]
	v_pk_mul_f32 v[48:49], v[48:49], v[236:237]
	v_pk_mul_f32 v[44:45], v[44:45], v[92:93]
	v_pk_mul_f32 v[40:41], v[40:41], v[228:229]
	v_pk_mul_f32 v[36:37], v[36:37], v[232:233]
	v_pk_mul_f32 v[46:47], v[46:47], v[94:95]
	v_pk_mul_f32 v[42:43], v[42:43], v[230:231]
	v_pk_mul_f32 v[38:39], v[38:39], v[234:235]
	v_pk_mul_f32 v[34:35], v[34:35], v[238:239]
	v_pk_mul_f32 v[32:33], v[32:33], v[236:237]
	v_pk_mul_f32 v[28:29], v[28:29], v[92:93]
	v_pk_mul_f32 v[24:25], v[24:25], v[228:229]
	v_pk_mul_f32 v[20:21], v[20:21], v[232:233]
	v_pk_mul_f32 v[30:31], v[30:31], v[94:95]
	v_pk_mul_f32 v[26:27], v[26:27], v[230:231]
	v_pk_mul_f32 v[22:23], v[22:23], v[234:235]
	v_pk_mul_f32 v[18:19], v[18:19], v[238:239]
	v_pk_mul_f32 v[16:17], v[16:17], v[236:237]

; #define QSTEP(d, A, B, NA, NB) do { if ((d) + 2 < 12) { NA = KLD((d) + 2, 0); NB = KLD((d) + 2, 1); } SBAR(); \
;     p0 = __builtin_amdgcn_mfma_f32_32x32x16_bf16(A, qr[d], p0, 0, 0, 0); p1 = __builtin_amdgcn_mfma_f32_32x32x16_bf16(B, qr[d], p1, 0, 0, 0); SBAR(); } while (0)
; __device__ __forceinline__ void partialSM(f32x16& p0, f32x16& p1, float& m_reg, float& mn, float& alpha) {
;   constexpr float C = SCALE * 1.4426950408889634f;
;   float pmax = p0[0];
; #pragma unroll
;   for (int r = 1; r < 16; ++r) pmax = fmaxf(pmax, p0[r]);
; #pragma unroll
;   for (int r = 0; r < 16; ++r) pmax = fmaxf(pmax, p1[r]);
;   { auto rr = __builtin_amdgcn_permlane32_swap(__float_as_uint(pmax), __float_as_uint(pmax), false, false);
;     pmax = fmaxf(__uint_as_float(rr[0]), __uint_as_float(rr[1])); }
;   if (__builtin_expect(__all(pmax - m_reg <= THR / SCALE), 1)) { mn = m_reg; alpha = 1.f; }
;   else { mn = fmaxf(m_reg, pmax); alpha = __builtin_amdgcn_exp2f((m_reg - mn) * C); m_reg = mn; }
; __device__ __forceinline__ void qkt2(f32x16& p0, f32x16& p1, const char* Ks, const bf16x8* qr, const int* kb4) {
;     ...
;   p0 = f32x16{}; p1 = f32x16{};
;   bf16x8 a0 = KLD(0, 0), b0 = KLD(0, 1), a1 = KLD(1, 0), b1 = KLD(1, 1), a2, b2;
;     ...
;   QSTEP(0, a0, b0, a2, b2); QSTEP(1, a1, b1, a0, b0); QSTEP(2, a2, b2, a1, b1);
;   QSTEP(3, a0, b0, a2, b2); QSTEP(4, a1, b1, a0, b0); QSTEP(5, a2, b2, a1, b1);
;   QSTEP(6, a0, b0, a2, b2); QSTEP(7, a1, b1, a0, b0); QSTEP(8, a2, b2, a1, b1);
;   QSTEP(9, a0, b0, a2, b2); QSTEP(10, a1, b1, a0, b0); QSTEP(11, a2, b2, a1, b1);
.Lb2_skip2:
	s_waitcnt lgkmcnt(7)
	v_mfma_f32_32x32x16_bf16 v[80:95], v[236:239], v[108:111], v[80:95]
	v_mfma_f32_32x32x16_bf16 v[64:79], v[240:243], v[108:111], v[64:79]
	ds_read_b128 v[236:239], v208 offset:57472
	ds_read_b128 v[240:243], v218 offset:12416
	s_cbranch_scc1 .LBB0_447
	global_load_dwordx4 v[180:183], v[146:147], off offset:256
.LBB0_447:
	s_waitcnt lgkmcnt(5)
	v_mfma_f32_32x32x16_bf16 v[80:95], v[194:197], v[112:115], v[80:95]
	v_mfma_f32_32x32x16_bf16 v[64:79], v[224:227], v[112:115], v[64:79]
	ds_read_b128 v[194:197], v207 offset:57472
	ds_read_b128 v[224:227], v219 offset:12416
	s_waitcnt lgkmcnt(4)
	v_mfma_f32_32x32x16_bf16 v[80:95], v[228:231], v[116:119], v[80:95]
	v_mfma_f32_32x32x16_bf16 v[64:79], v[232:235], v[116:119], v[64:79]
	ds_read_b128 v[228:231], v210 offset:57600
	ds_read_b128 v[232:235], v216 offset:12544
	s_waitcnt lgkmcnt(4)
	v_mfma_f32_32x32x16_bf16 v[80:95], v[236:239], v[120:123], v[80:95]
	v_mfma_f32_32x32x16_bf16 v[64:79], v[240:243], v[120:123], v[64:79]
	ds_read_b128 v[236:239], v209 offset:57600
	ds_read_b128 v[240:243], v217 offset:12544
	s_waitcnt lgkmcnt(4)
	v_mfma_f32_32x32x16_bf16 v[80:95], v[194:197], v[124:127], v[80:95]
	v_mfma_f32_32x32x16_bf16 v[64:79], v[224:227], v[124:127], v[64:79]
	ds_read_b128 v[194:197], v208 offset:57600
	ds_read_b128 v[224:227], v218 offset:12544
	s_waitcnt lgkmcnt(4)
	v_mfma_f32_32x32x16_bf16 v[80:95], v[228:231], v[132:135], v[80:95]
	v_mfma_f32_32x32x16_bf16 v[64:79], v[232:235], v[132:135], v[64:79]
	ds_read_b128 v[228:231], v207 offset:57600
	ds_read_b128 v[232:235], v219 offset:12544
	s_waitcnt lgkmcnt(4)
	v_mfma_f32_32x32x16_bf16 v[80:95], v[236:239], v[140:143], v[80:95]
	v_mfma_f32_32x32x16_bf16 v[64:79], v[240:243], v[140:143], v[64:79]
	s_waitcnt lgkmcnt(2)
	v_mfma_f32_32x32x16_bf16 v[80:95], v[194:197], v[128:131], v[80:95]
	v_mfma_f32_32x32x16_bf16 v[64:79], v[224:227], v[128:131], v[64:79]
	s_waitcnt lgkmcnt(0)
	v_mfma_f32_32x32x16_bf16 v[80:95], v[228:231], v[136:139], v[80:95]
	v_mfma_f32_32x32x16_bf16 v[64:79], v[232:235], v[136:139], v[64:79]
	s_nop 9
	v_max_f32_e32 v194, v81, v81
	v_max_f32_e32 v195, v80, v80
	v_max_f32_e32 v194, v195, v194
	v_max3_f32 v194, v194, v82, v83
	v_max3_f32 v194, v194, v84, v85
	v_max3_f32 v194, v194, v86, v87
	v_max3_f32 v194, v194, v88, v89
	v_max3_f32 v194, v194, v90, v91
	v_max3_f32 v194, v194, v92, v93
	v_max3_f32 v194, v194, v94, v95
	v_max3_f32 v194, v194, v64, v65
	v_max3_f32 v194, v194, v66, v67
	v_max3_f32 v194, v194, v68, v69
	v_max3_f32 v194, v194, v70, v71
	v_max3_f32 v194, v194, v72, v73
	v_max3_f32 v194, v194, v74, v75
	v_max3_f32 v194, v194, v76, v77
	v_max3_f32 v194, v194, v78, v79
	v_mov_b32_e32 v195, v194
	s_nop 1
	v_permlane32_swap_b32_e32 v194, v195
	v_max_f32_e32 v195, v195, v195
	v_max_f32_e32 v194, v194, v194
	v_max_f32_e32 v194, v194, v195
	v_max_f32_e32 v195, v220, v220
	v_max_f32_e32 v195, v195, v194
	v_sub_f32_e32 v196, v194, v220
	v_sub_f32_e32 v194, v220, v195
	v_mul_f32_e32 v194, 0x3dd53b94, v194
	v_exp_f32_e32 v194, v194
	v_cmp_ge_f32_e32 vcc, s30, v196
	s_cmp_eq_u64 vcc, exec
	s_cselect_b64 s[8:9], -1, 0
	s_waitcnt lgkmcnt(0)
	s_barrier
	v_cndmask_b32_e64 v194, v194, 1.0, s[8:9]
	v_cmp_gt_f32_e32 vcc, 1.0, v194
	s_cbranch_vccz .LBB0_451
	s_and_saveexec_b64 s[0:1], s[6:7]
	ds_write_b32 v205, v194 offset:128
	s_or_b64 exec, exec, s[0:1]
	s_waitcnt lgkmcnt(0)
	v_add_u32_e32 v196, s3, v184
	ds_read_b128 v[224:227], v196 offset:224
	ds_read_b128 v[228:231], v196 offset:192
	ds_read_b128 v[232:235], v196 offset:160
	ds_read_b128 v[236:239], v196 offset:128
	s_waitcnt lgkmcnt(3)
	v_pk_mul_f32 v[12:13], v[12:13], v[224:225]
	s_waitcnt lgkmcnt(2)
	v_pk_mul_f32 v[8:9], v[8:9], v[228:229]
	s_waitcnt lgkmcnt(1)
	v_pk_mul_f32 v[4:5], v[4:5], v[232:233]
	v_pk_mul_f32 v[14:15], v[14:15], v[226:227]
	v_pk_mul_f32 v[10:11], v[10:11], v[230:231]
	v_pk_mul_f32 v[6:7], v[6:7], v[234:235]
	s_waitcnt lgkmcnt(0)
	v_pk_mul_f32 v[2:3], v[2:3], v[238:239]
	v_pk_mul_f32 v[0:1], v[0:1], v[236:237]
	v_pk_mul_f32 v[60:61], v[60:61], v[224:225]
	v_pk_mul_f32 v[56:57], v[56:57], v[228:229]
	v_pk_mul_f32 v[52:53], v[52:53], v[232:233]
	v_pk_mul_f32 v[62:63], v[62:63], v[226:227]
	v_pk_mul_f32 v[58:59], v[58:59], v[230:231]
	v_pk_mul_f32 v[54:55], v[54:55], v[234:235]
	v_pk_mul_f32 v[50:51], v[50:51], v[238:239]
	v_pk_mul_f32 v[48:49], v[48:49], v[236:237]
	v_pk_mul_f32 v[44:45], v[44:45], v[224:225]
	v_pk_mul_f32 v[40:41], v[40:41], v[228:229]
	v_pk_mul_f32 v[36:37], v[36:37], v[232:233]
	v_pk_mul_f32 v[46:47], v[46:47], v[226:227]
	v_pk_mul_f32 v[42:43], v[42:43], v[230:231]
	v_pk_mul_f32 v[38:39], v[38:39], v[234:235]
	v_pk_mul_f32 v[34:35], v[34:35], v[238:239]
	v_pk_mul_f32 v[32:33], v[32:33], v[236:237]
	v_pk_mul_f32 v[28:29], v[28:29], v[224:225]
	v_pk_mul_f32 v[24:25], v[24:25], v[228:229]
	v_pk_mul_f32 v[20:21], v[20:21], v[232:233]
	v_pk_mul_f32 v[30:31], v[30:31], v[226:227]
	v_pk_mul_f32 v[26:27], v[26:27], v[230:231]
	v_pk_mul_f32 v[22:23], v[22:23], v[234:235]
	v_pk_mul_f32 v[18:19], v[18:19], v[238:239]
	v_pk_mul_f32 v[16:17], v[16:17], v[236:237]

; #define SLOAD(t) do { const long r0_ = TROW(t); const bf16_t* vp_ = Vh + r0_ * LDV + vgo0; const bf16_t* kp_ = Kh + r0_ * LDKK + kgo0; \
;     vs0 = *reinterpret_cast<const bf16x8*>(vp_); vs1 = *reinterpret_cast<const bf16x8*>(vp_ + 64); \
;     ks0 = *reinterpret_cast<const bf16x8*>(kp_); ks1 = *reinterpret_cast<const bf16x8*>(kp_ + 64); ks2 = *reinterpret_cast<const bf16x8*>(kp_ + 128); } while (0)
; #define SWRITE(b) do { *(bf16x8*)(V_lds + (b) * SHM_V + vst0) = vs0; *(bf16x8*)(V_lds + (b) * SHM_V + vst0 + 1024) = vs1; \
;     *(bf16x8*)(K_lds + (b) * SHM_K + klo0) = ks0; *(bf16x8*)(K_lds + (b) * SHM_K + klo0 + 128) = ks1; *(bf16x8*)(K_lds + (b) * SHM_K + klo0 + 256) = ks2; } while (0)
; #define SWAIT() asm volatile("s_waitcnt vmcnt(0)" ::: "memory")
; #define SLOAD(t) do { const long r0_ = TROW(t); const bf16_t* vp_ = Vh + r0_ * LDV + vgo0; const bf16_t* kp_ = Kh + r0_ * LDKK + kgo0; \
;     vs0 = *reinterpret_cast<const bf16x8*>(vp_); vs1 = *reinterpret_cast<const bf16x8*>(vp_ + 64); \
;     ks0 = *reinterpret_cast<const bf16x8*>(kp_); ks1 = *reinterpret_cast<const bf16x8*>(kp_ + 64); ks2 = *reinterpret_cast<const bf16x8*>(kp_ + 128); } while (0)
; #define SWRITE(b) do { *(bf16x8*)(V_lds + (b) * SHM_V + vst0) = vs0; *(bf16x8*)(V_lds + (b) * SHM_V + vst0 + 1024) = vs1; \
;     *(bf16x8*)(K_lds + (b) * SHM_K + klo0) = ks0; *(bf16x8*)(K_lds + (b) * SHM_K + klo0 + 128) = ks1; *(bf16x8*)(K_lds + (b) * SHM_K + klo0 + 256) = ks2; } while (0)
; #define SWAIT() asm volatile("s_waitcnt vmcnt(0)" ::: "memory")
; #define BARRIER() asm volatile("s_waitcnt lgkmcnt(0)\n\ts_barrier" ::: "memory")
; __device__ __forceinline__ void partialSM(f32x16& p0, f32x16& p1, float& m_reg, float& mn, float& alpha) {
;   constexpr float C = SCALE * 1.4426950408889634f;
;   float pmax = p0[0];
; #pragma unroll
;   for (int r = 1; r < 16; ++r) pmax = fmaxf(pmax, p0[r]);
; #pragma unroll
;   for (int r = 0; r < 16; ++r) pmax = fmaxf(pmax, p1[r]);
; __device__ __forceinline__ void attn_unit2(const bf16_t* __restrict__ Qb, const bf16_t* __restrict__ Kh, const bf16_t* __restrict__ Vh, ...
;     ...
;   f32x16 p0, p1; float mn, al = 1.f; bf16x8 pa0, pa1, pa2, pa3; constexpr int NT = NCHUNK;
;   SLOAD(0); SWAIT(); SWRITE(0); BARRIER();
.Lmask0_b:
	s_mov_b64 vcc, -1
	s_nop 7
	v_cndmask_b32_e32 v222, v76, v201, vcc
	v_cndmask_b32_e32 v223, v77, v201, vcc
	v_cndmask_b32_e32 v76, v90, v201, vcc
	v_cndmask_b32_e32 v77, v91, v201, vcc
	v_max_f32_e32 v90, v65, v65
	v_max_f32_e32 v91, v64, v64
	v_max_f32_e32 v90, v91, v90
	v_max3_f32 v90, v90, v66, v67
	v_max3_f32 v90, v90, v68, v69
	v_cndmask_b32_e32 v226, v72, v201, vcc
	v_cndmask_b32_e32 v227, v73, v201, vcc
	v_max3_f32 v90, v90, v70, v71
	v_cndmask_b32_e32 v224, v74, v201, vcc
	v_cndmask_b32_e32 v225, v75, v201, vcc
	v_max3_f32 v90, v90, v226, v227
	v_max3_f32 v90, v90, v224, v225
	v_cndmask_b32_e32 v78, v78, v201, vcc
	v_cndmask_b32_e32 v79, v79, v201, vcc
	v_max3_f32 v90, v90, v222, v223
	v_cndmask_b32_e32 v80, v80, v201, vcc
	v_cndmask_b32_e32 v81, v81, v201, vcc
	v_max3_f32 v90, v90, v78, v79
	v_cndmask_b32_e32 v82, v82, v201, vcc
	v_cndmask_b32_e32 v83, v83, v201, vcc
	v_max3_f32 v90, v90, v80, v81
	v_cndmask_b32_e32 v84, v84, v201, vcc
	v_cndmask_b32_e32 v85, v85, v201, vcc
	v_max3_f32 v90, v90, v82, v83
	v_cndmask_b32_e32 v86, v86, v201, vcc
	v_cndmask_b32_e32 v87, v87, v201, vcc
	v_max3_f32 v90, v90, v84, v85
	v_cndmask_b32_e32 v88, v88, v201, vcc
	v_cndmask_b32_e32 v89, v89, v201, vcc
	v_max3_f32 v90, v90, v86, v87
	v_max3_f32 v90, v90, v88, v89
	v_cndmask_b32_e32 v74, v92, v201, vcc
	v_cndmask_b32_e32 v75, v93, v201, vcc
	v_max3_f32 v90, v90, v76, v77
	v_cndmask_b32_e32 v73, v94, v201, vcc
	v_cndmask_b32_e32 v72, v95, v201, vcc
	v_max3_f32 v90, v90, v74, v75
	v_max3_f32 v90, v90, v73, v72
	s_branch .Lback0_b

; #define SLOAD(t) do { const long r0_ = TROW(t); const bf16_t* vp_ = Vh + r0_ * LDV + vgo0; const bf16_t* kp_ = Kh + r0_ * LDKK + kgo0; \
;     vs0 = *reinterpret_cast<const bf16x8*>(vp_); vs1 = *reinterpret_cast<const bf16x8*>(vp_ + 64); \
;     ks0 = *reinterpret_cast<const bf16x8*>(kp_); ks1 = *reinterpret_cast<const bf16x8*>(kp_ + 64); ks2 = *reinterpret_cast<const bf16x8*>(kp_ + 128); } while (0)
; #define SWRITE(b) do { *(bf16x8*)(V_lds + (b) * SHM_V + vst0) = vs0; *(bf16x8*)(V_lds + (b) * SHM_V + vst0 + 1024) = vs1; \
;     *(bf16x8*)(K_lds + (b) * SHM_K + klo0) = ks0; *(bf16x8*)(K_lds + (b) * SHM_K + klo0 + 128) = ks1; *(bf16x8*)(K_lds + (b) * SHM_K + klo0 + 256) = ks2; } while (0)
; #define SWAIT() asm volatile("s_waitcnt vmcnt(0)" ::: "memory")
; #define SLOAD(t) do { const long r0_ = TROW(t); const bf16_t* vp_ = Vh + r0_ * LDV + vgo0; const bf16_t* kp_ = Kh + r0_ * LDKK + kgo0; \
;     vs0 = *reinterpret_cast<const bf16x8*>(vp_); vs1 = *reinterpret_cast<const bf16x8*>(vp_ + 64); \
;     ks0 = *reinterpret_cast<const bf16x8*>(kp_); ks1 = *reinterpret_cast<const bf16x8*>(kp_ + 64); ks2 = *reinterpret_cast<const bf16x8*>(kp_ + 128); } while (0)
; #define SWAIT() asm volatile("s_waitcnt vmcnt(0)" ::: "memory")
; #define BARRIER() asm volatile("s_waitcnt lgkmcnt(0)\n\ts_barrier" ::: "memory")
; __device__ __forceinline__ void partialSM(f32x16& p0, f32x16& p1, float& m_reg, float& mn, float& alpha) {
;   constexpr float C = SCALE * 1.4426950408889634f;
;   float pmax = p0[0];
; #pragma unroll
;   for (int r = 1; r < 16; ++r) pmax = fmaxf(pmax, p0[r]);
; #pragma unroll
;   for (int r = 0; r < 16; ++r) pmax = fmaxf(pmax, p1[r]);
;   { auto rr = __builtin_amdgcn_permlane32_swap(__float_as_uint(pmax), __float_as_uint(pmax), false, false);
;     pmax = fmaxf(__uint_as_float(rr[0]), __uint_as_float(rr[1])); }
;   if (__builtin_expect(__all(pmax - m_reg <= THR / SCALE), 1)) { mn = m_reg; alpha = 1.f; }
;   else { mn = fmaxf(m_reg, pmax); alpha = __builtin_amdgcn_exp2f((m_reg - mn) * C); m_reg = mn; }
; __device__ __forceinline__ void attn_unit2(const bf16_t* __restrict__ Qb, const bf16_t* __restrict__ Kh, const bf16_t* __restrict__ Vh, ...
;     ...
;   f32x16 p0, p1; float mn, al = 1.f; bf16x8 pa0, pa1, pa2, pa3; constexpr int NT = NCHUNK;
;   SLOAD(0); SWAIT(); SWRITE(0); BARRIER();
;     ...
;   if (wid < 4) {
.LBB0_459:
	ds_read_b128 v[64:67], v210 offset:32768
	ds_read_b128 v[80:83], v210 offset:45056
	ds_read_b128 v[168:171], v209 offset:32768
	ds_read_b128 v[180:183], v209 offset:45056
	ds_read_b128 v[186:189], v208 offset:32768
	ds_read_b128 v[190:193], v208 offset:45056
	s_waitcnt lgkmcnt(4)
	v_mfma_f32_32x32x16_bf16 v[64:79], v[64:67], v[96:99], 0
	v_mfma_f32_32x32x16_bf16 v[80:95], v[80:83], v[96:99], 0
	ds_read_b128 v[194:197], v207 offset:32768
	ds_read_b128 v[214:217], v207 offset:45056
	s_waitcnt lgkmcnt(4)
	v_mfma_f32_32x32x16_bf16 v[64:79], v[168:171], v[100:103], v[64:79]
	v_mfma_f32_32x32x16_bf16 v[80:95], v[180:183], v[100:103], v[80:95]
	ds_read_b128 v[168:171], v210 offset:32896
	ds_read_b128 v[180:183], v210 offset:45184
	s_waitcnt lgkmcnt(4)
	v_mfma_f32_32x32x16_bf16 v[64:79], v[186:189], v[104:107], v[64:79]
	v_mfma_f32_32x32x16_bf16 v[80:95], v[190:193], v[104:107], v[80:95]
	ds_read_b128 v[186:189], v209 offset:32896
	ds_read_b128 v[190:193], v209 offset:45184
	s_waitcnt lgkmcnt(4)
	v_mfma_f32_32x32x16_bf16 v[64:79], v[194:197], v[108:111], v[64:79]
	v_mfma_f32_32x32x16_bf16 v[80:95], v[214:217], v[108:111], v[80:95]
	ds_read_b128 v[194:197], v208 offset:32896
	ds_read_b128 v[214:217], v208 offset:45184
	s_waitcnt lgkmcnt(4)
	v_mfma_f32_32x32x16_bf16 v[64:79], v[168:171], v[112:115], v[64:79]
	v_mfma_f32_32x32x16_bf16 v[80:95], v[180:183], v[112:115], v[80:95]
	ds_read_b128 v[168:171], v207 offset:32896
	ds_read_b128 v[180:183], v207 offset:45184
	s_waitcnt lgkmcnt(4)
	v_mfma_f32_32x32x16_bf16 v[64:79], v[186:189], v[116:119], v[64:79]
	v_mfma_f32_32x32x16_bf16 v[80:95], v[190:193], v[116:119], v[80:95]
	ds_read_b128 v[186:189], v210 offset:33024
	ds_read_b128 v[190:193], v210 offset:45312
	s_waitcnt lgkmcnt(4)
	v_mfma_f32_32x32x16_bf16 v[64:79], v[194:197], v[120:123], v[64:79]
	v_mfma_f32_32x32x16_bf16 v[80:95], v[214:217], v[120:123], v[80:95]
	ds_read_b128 v[194:197], v209 offset:33024
	ds_read_b128 v[214:217], v209 offset:45312
	s_waitcnt lgkmcnt(4)
	v_mfma_f32_32x32x16_bf16 v[64:79], v[168:171], v[124:127], v[64:79]
	v_mfma_f32_32x32x16_bf16 v[80:95], v[180:183], v[124:127], v[80:95]
	ds_read_b128 v[168:171], v208 offset:33024
	ds_read_b128 v[180:183], v208 offset:45312
	s_waitcnt lgkmcnt(4)
	v_mfma_f32_32x32x16_bf16 v[64:79], v[186:189], v[132:135], v[64:79]
	v_mfma_f32_32x32x16_bf16 v[80:95], v[190:193], v[132:135], v[80:95]
	ds_read_b128 v[186:189], v207 offset:33024
	ds_read_b128 v[190:193], v207 offset:45312
	s_waitcnt lgkmcnt(4)
	v_mfma_f32_32x32x16_bf16 v[64:79], v[194:197], v[140:143], v[64:79]
	v_mfma_f32_32x32x16_bf16 v[80:95], v[214:217], v[140:143], v[80:95]
	s_waitcnt lgkmcnt(2)
	v_mfma_f32_32x32x16_bf16 v[64:79], v[168:171], v[128:131], v[64:79]
	v_mfma_f32_32x32x16_bf16 v[80:95], v[180:183], v[128:131], v[80:95]
	s_waitcnt lgkmcnt(0)
	v_mfma_f32_32x32x16_bf16 v[64:79], v[186:189], v[136:139], v[64:79]
	v_mfma_f32_32x32x16_bf16 v[80:95], v[190:193], v[136:139], v[80:95]
	v_readlane_b32 s0, v247, 14
	v_readlane_b32 s1, v247, 15
	s_cmp_eq_u32 s42, 0
	s_cbranch_scc1 .Lmask0_a
	s_nop 7
	v_mov_b32_e32 v180, v76
	v_mov_b32_e32 v181, v77
	v_mov_b32_e32 v76, v90
	v_mov_b32_e32 v77, v91
	v_max_f32_e32 v90, v65, v65
	v_max_f32_e32 v91, v64, v64
	v_max_f32_e32 v90, v91, v90
	v_max3_f32 v90, v90, v66, v67
	v_max3_f32 v90, v90, v68, v69
	v_mov_b32_e32 v186, v72
	v_mov_b32_e32 v187, v73
	v_max3_f32 v90, v90, v70, v71
	v_mov_b32_e32 v182, v74
	v_mov_b32_e32 v183, v75
	v_max3_f32 v90, v90, v186, v187
	v_max3_f32 v90, v90, v182, v183
	v_max3_f32 v90, v90, v180, v181
	v_max3_f32 v90, v90, v78, v79
	v_max3_f32 v90, v90, v80, v81
	v_max3_f32 v90, v90, v82, v83
	v_max3_f32 v90, v90, v84, v85
	v_max3_f32 v90, v90, v86, v87
	v_max3_f32 v90, v90, v88, v89
	v_mov_b32_e32 v74, v92
	v_mov_b32_e32 v75, v93
	v_max3_f32 v90, v90, v76, v77
	v_mov_b32_e32 v73, v94
	v_mov_b32_e32 v72, v95
	v_max3_f32 v90, v90, v74, v75
	v_max3_f32 v90, v90, v73, v72
.Lback0_a:
	v_mov_b32_e32 v91, v90
	s_nop 1
	v_permlane32_swap_b32_e32 v90, v91
	v_max_f32_e32 v91, v91, v91
	v_max_f32_e32 v90, v90, v90
	v_max_f32_e32 v90, v90, v91
	v_max_f32_e32 v92, v178, v178
	v_sub_f32_e32 v91, v90, v178
	v_max_f32_e32 v90, v92, v90
	v_sub_f32_e32 v92, v178, v90
	v_mul_f32_e32 v92, 0x3dd53b94, v92
	v_exp_f32_e32 v92, v92
	v_cmp_ge_f32_e32 vcc, s30, v91
	s_cmp_eq_u64 vcc, exec
	s_cselect_b64 s[8:9], -1, 0
	s_waitcnt lgkmcnt(0)
	s_barrier
	s_waitcnt vmcnt(0)
	ds_write_b128 v212, v[144:147] offset:16384
	ds_write_b128 v212, v[148:151] offset:17408
	ds_write_b128 v211, v[152:155] offset:57344
	ds_write_b128 v211, v[156:159] offset:57472
	ds_write_b128 v211, v[160:163] offset:57600
	v_lshl_add_u64 v[170:171], s[52:53], 0, v[166:167]
	v_add_co_u32_e32 v148, vcc, s28, v170
	v_lshl_add_u64 v[168:169], s[52:53], 0, v[164:165]
	s_nop 0
	v_addc_co_u32_e32 v149, vcc, 0, v171, vcc
	v_add_co_u32_e32 v160, vcc, 0x1b330000, v168
	global_load_dwordx4 v[144:147], v[148:149], off offset:256
	s_nop 0
	global_load_dwordx4 v[148:151], v[148:149], off offset:384
	v_addc_co_u32_e32 v161, vcc, 0, v169, vcc
	global_load_dwordx4 v[152:155], v[160:161], off
	global_load_dwordx4 v[156:159], v[160:161], off offset:128
	s_nop 0
	global_load_dwordx4 v[160:163], v[160:161], off offset:256
	v_cndmask_b32_e64 v179, v92, 1.0, s[8:9]
	v_cmp_gt_f32_e32 vcc, 1.0, v179
	s_cbranch_vccz .LBB0_463
; #define SBAR() __builtin_amdgcn_sched_barrier(0)
; __device__ __forceinline__ void finishSM(f32x16& p0, f32x16& p1, float alpha, float& l_reg, bf16x8& pa0, bf16x8& pa1, bf16x8& pa2, bf16x8& pa3) {
; #pragma unroll
;   for (int r = 0; r < 16; ++r) p1[r] = __builtin_amdgcn_exp2f(p1[r]);
;   float ps = 0;
; #pragma unroll
;   for (int r = 0; r < 16; ++r) ps += p0[r];
; #pragma unroll
;   for (int r = 0; r < 16; ++r) ps += p1[r];
;   { auto rr = __builtin_amdgcn_permlane32_swap(__float_as_uint(ps), __float_as_uint(ps), false, false);
;     ps = __uint_as_float(rr[0]) + __uint_as_float(rr[1]); }
;   l_reg = l_reg * alpha + ps;
;     ...
;   PK4(p0, 0, pa0); PK4(p0, 8, pa1); PK4(p1, 0, pa2); PK4(p1, 8, pa3);
;     ...
; }
; __device__ __forceinline__ void pv2(f32x16* o, int vb, bf16x8 pa0, bf16x8 pa1, bf16x8 pa2, bf16x8 pa3) {
;   VSet X, Y;
;   SBAR(); v_issue<0>(X, vb); v_issue<1>(Y, vb);
	s_and_saveexec_b64 s[0:1], s[6:7]
	ds_write_b32 v205, v179 offset:128
	s_or_b64 exec, exec, s[0:1]
	s_waitcnt lgkmcnt(0)
	v_add_u32_e32 v91, s3, v184
	ds_read_b128 v[92:95], v91 offset:224
	ds_read_b128 v[188:191], v91 offset:192
	ds_read_b128 v[192:195], v91 offset:160
	ds_read_b128 v[214:217], v91 offset:128
	s_waitcnt lgkmcnt(3)
	v_pk_mul_f32 v[12:13], v[12:13], v[92:93]
	s_waitcnt lgkmcnt(2)
	v_pk_mul_f32 v[8:9], v[8:9], v[188:189]
	s_waitcnt lgkmcnt(1)
	v_pk_mul_f32 v[4:5], v[4:5], v[192:193]
	v_pk_mul_f32 v[14:15], v[14:15], v[94:95]
	v_pk_mul_f32 v[10:11], v[10:11], v[190:191]
	v_pk_mul_f32 v[6:7], v[6:7], v[194:195]
	s_waitcnt lgkmcnt(0)
	v_pk_mul_f32 v[2:3], v[2:3], v[216:217]
	v_pk_mul_f32 v[0:1], v[0:1], v[214:215]
	v_pk_mul_f32 v[60:61], v[60:61], v[92:93]
	v_pk_mul_f32 v[56:57], v[56:57], v[188:189]
	v_pk_mul_f32 v[52:53], v[52:53], v[192:193]
	v_pk_mul_f32 v[62:63], v[62:63], v[94:95]
	v_pk_mul_f32 v[58:59], v[58:59], v[190:191]
	v_pk_mul_f32 v[54:55], v[54:55], v[194:195]
	v_pk_mul_f32 v[50:51], v[50:51], v[216:217]
	v_pk_mul_f32 v[48:49], v[48:49], v[214:215]
	v_pk_mul_f32 v[44:45], v[44:45], v[92:93]
	v_pk_mul_f32 v[40:41], v[40:41], v[188:189]
	v_pk_mul_f32 v[36:37], v[36:37], v[192:193]
	v_pk_mul_f32 v[46:47], v[46:47], v[94:95]
	v_pk_mul_f32 v[42:43], v[42:43], v[190:191]
	v_pk_mul_f32 v[38:39], v[38:39], v[194:195]
	v_pk_mul_f32 v[34:35], v[34:35], v[216:217]
	v_pk_mul_f32 v[32:33], v[32:33], v[214:215]
	v_pk_mul_f32 v[28:29], v[28:29], v[92:93]
	v_pk_mul_f32 v[24:25], v[24:25], v[188:189]
	v_pk_mul_f32 v[20:21], v[20:21], v[192:193]
	v_pk_mul_f32 v[30:31], v[30:31], v[94:95]
	v_pk_mul_f32 v[26:27], v[26:27], v[190:191]
	v_pk_mul_f32 v[22:23], v[22:23], v[194:195]
	v_pk_mul_f32 v[18:19], v[18:19], v[216:217]
	v_pk_mul_f32 v[16:17], v[16:17], v[214:215]
.LBB0_463:
	v_cndmask_b32_e64 v178, v90, v178, s[8:9]
	v_mul_f32_e32 v90, 0xbdd53b94, v178
	v_fmamk_f32 v64, v64, 0x3dd53b94, v90
	v_fmamk_f32 v65, v65, 0x3dd53b94, v90
	v_exp_f32_e32 v64, v64
	v_fmamk_f32 v66, v66, 0x3dd53b94, v90
	v_exp_f32_e32 v65, v65
	v_fmamk_f32 v67, v67, 0x3dd53b94, v90
	v_exp_f32_e32 v66, v66
	v_fmamk_f32 v68, v68, 0x3dd53b94, v90
	v_fmamk_f32 v73, v73, 0x3dd53b94, v90
	v_exp_f32_e32 v67, v67
	v_fmamk_f32 v69, v69, 0x3dd53b94, v90
	v_fmamk_f32 v92, v187, 0x3dd53b94, v90
	v_exp_f32_e32 v68, v68
	v_exp_f32_e32 v187, v73
	v_add_f32_e32 v73, 0, v64
	v_fmamk_f32 v70, v70, 0x3dd53b94, v90
	v_exp_f32_e32 v69, v69
	v_add_f32_e32 v73, v65, v73
	v_fmamk_f32 v71, v71, 0x3dd53b94, v90
	v_exp_f32_e32 v70, v70
	v_add_f32_e32 v73, v66, v73
	v_fmamk_f32 v91, v186, 0x3dd53b94, v90
	v_exp_f32_e32 v71, v71
	v_add_f32_e32 v73, v67, v73
	v_fmamk_f32 v93, v182, 0x3dd53b94, v90
	v_fmamk_f32 v94, v183, 0x3dd53b94, v90
	v_fmamk_f32 v95, v180, 0x3dd53b94, v90
	v_fmamk_f32 v180, v181, 0x3dd53b94, v90
	v_fmamk_f32 v78, v78, 0x3dd53b94, v90
	v_fmamk_f32 v79, v79, 0x3dd53b94, v90
	v_fmamk_f32 v80, v80, 0x3dd53b94, v90
	v_fmamk_f32 v81, v81, 0x3dd53b94, v90
	v_fmamk_f32 v82, v82, 0x3dd53b94, v90
	v_fmamk_f32 v83, v83, 0x3dd53b94, v90
	v_fmamk_f32 v84, v84, 0x3dd53b94, v90
	v_fmamk_f32 v85, v85, 0x3dd53b94, v90
	v_fmamk_f32 v86, v86, 0x3dd53b94, v90
	v_fmamk_f32 v87, v87, 0x3dd53b94, v90
	v_fmamk_f32 v88, v88, 0x3dd53b94, v90
	v_fmamk_f32 v89, v89, 0x3dd53b94, v90
	v_fmamk_f32 v76, v76, 0x3dd53b94, v90
	v_fmamk_f32 v77, v77, 0x3dd53b94, v90
	v_fmamk_f32 v74, v74, 0x3dd53b94, v90
	v_fmamk_f32 v75, v75, 0x3dd53b94, v90
	v_fmac_f32_e32 v90, 0x3dd53b94, v72
	v_exp_f32_e32 v72, v91
	v_add_f32_e32 v73, v68, v73
	v_exp_f32_e32 v91, v92
	v_add_f32_e32 v73, v69, v73
	v_exp_f32_e32 v92, v93
	v_add_f32_e32 v73, v70, v73
	v_exp_f32_e32 v93, v94
	v_add_f32_e32 v73, v71, v73
	v_exp_f32_e32 v94, v95
	v_add_f32_e32 v73, v72, v73
	v_exp_f32_e32 v95, v180
	v_add_f32_e32 v73, v91, v73
	v_exp_f32_e32 v78, v78
	v_add_f32_e32 v73, v92, v73
	v_exp_f32_e32 v79, v79
	v_add_f32_e32 v73, v93, v73
	v_exp_f32_e32 v80, v80
	v_add_f32_e32 v73, v94, v73
	v_exp_f32_e32 v81, v81
	v_add_f32_e32 v73, v95, v73
	v_exp_f32_e32 v82, v82
	v_add_f32_e32 v73, v78, v73
	v_exp_f32_e32 v83, v83
	v_add_f32_e32 v73, v79, v73
	v_exp_f32_e32 v84, v84
	v_add_f32_e32 v73, v80, v73
	v_exp_f32_e32 v85, v85
	v_add_f32_e32 v73, v81, v73
	v_exp_f32_e32 v86, v86
	v_add_f32_e32 v73, v82, v73
	v_exp_f32_e32 v87, v87
	v_add_f32_e32 v73, v83, v73
	v_exp_f32_e32 v88, v88
	v_add_f32_e32 v73, v84, v73
	v_exp_f32_e32 v89, v89
	v_add_f32_e32 v73, v85, v73
	v_exp_f32_e32 v182, v76
	v_add_f32_e32 v73, v86, v73
	v_exp_f32_e32 v77, v77
	v_add_f32_e32 v73, v87, v73
	v_exp_f32_e32 v183, v74
	v_add_f32_e32 v73, v88, v73
	v_exp_f32_e32 v186, v75
	v_add_f32_e32 v73, v89, v73
	v_add_f32_e32 v73, v182, v73
	v_exp_f32_e32 v90, v90
	v_add_f32_e32 v73, v77, v73
	v_add_f32_e32 v73, v183, v73
	v_add_f32_e32 v73, v186, v73
	v_add_f32_e32 v73, v187, v73
	v_add_f32_e32 v180, v90, v73
	v_mov_b32_e32 v181, v180
	v_cvt_pk_bf16_f32 v64, v64, v65
	v_cvt_pk_bf16_f32 v65, v66, v67
	v_cvt_pk_bf16_f32 v66, v68, v69
	v_cvt_pk_bf16_f32 v67, v70, v71
	v_cvt_pk_bf16_f32 v68, v72, v91
	v_cvt_pk_bf16_f32 v69, v92, v93
	v_cvt_pk_bf16_f32 v70, v94, v95
	v_cvt_pk_bf16_f32 v71, v78, v79
	v_cvt_pk_bf16_f32 v72, v80, v81
	v_cvt_pk_bf16_f32 v73, v82, v83
	v_cvt_pk_bf16_f32 v74, v84, v85
	v_cvt_pk_bf16_f32 v75, v86, v87
	v_cvt_pk_bf16_f32 v76, v88, v89
	v_cvt_pk_bf16_f32 v77, v182, v77
	v_cvt_pk_bf16_f32 v78, v183, v186
	v_cvt_pk_bf16_f32 v79, v187, v90
	s_nop 1
	v_permlane32_swap_b32_e32 v180, v181
	v_permlane32_swap_b32_e32 v64, v66
	v_permlane32_swap_b32_e32 v65, v67
	v_permlane32_swap_b32_e32 v68, v70
	v_permlane32_swap_b32_e32 v69, v71
	v_permlane32_swap_b32_e32 v72, v74
	v_permlane32_swap_b32_e32 v73, v75
	v_permlane32_swap_b32_e32 v76, v78
	v_permlane32_swap_b32_e32 v77, v79
	ds_read_b64_tr_b16 v[80:81], v206 offset:0
	ds_read_b64_tr_b16 v[82:83], v206 offset:0x800
	ds_read_b64_tr_b16 v[84:85], v206 offset:0x1000
	ds_read_b64_tr_b16 v[86:87], v206 offset:0x1800
	ds_read_b64_tr_b16 v[88:89], v206 offset:0x2000
	ds_read_b64_tr_b16 v[90:91], v206 offset:0x2800
	ds_read_b64_tr_b16 v[92:93], v206 offset:0x3000
	ds_read_b64_tr_b16 v[94:95], v206 offset:0x3800
	ds_read_b64_tr_b16 v[186:187], v206 offset:0x200
	ds_read_b64_tr_b16 v[188:189], v206 offset:0xa00
	ds_read_b64_tr_b16 v[190:191], v206 offset:0x1200
	ds_read_b64_tr_b16 v[192:193], v206 offset:0x1a00
	ds_read_b64_tr_b16 v[194:195], v206 offset:0x2200
	ds_read_b64_tr_b16 v[196:197], v206 offset:0x2a00
	ds_read_b64_tr_b16 v[214:215], v206 offset:0x3200
	ds_read_b64_tr_b16 v[216:217], v206 offset:0x3a00
	s_waitcnt lgkmcnt(8)
; #define SBAR() __builtin_amdgcn_sched_barrier(0)
; #define QSTEP(d, A, B, NA, NB) do { if ((d) + 2 < 12) { NA = KLD((d) + 2, 0); NB = KLD((d) + 2, 1); } SBAR(); \
;     p0 = __builtin_amdgcn_mfma_f32_32x32x16_bf16(A, qr[d], p0, 0, 0, 0); p1 = __builtin_amdgcn_mfma_f32_32x32x16_bf16(B, qr[d], p1, 0, 0, 0); SBAR(); } while (0)
; __device__ __forceinline__ void qkt2(f32x16& p0, f32x16& p1, const char* Ks, const bf16x8* qr, const int* kb4) {
;     ...
;   p0 = f32x16{}; p1 = f32x16{};
;   bf16x8 a0 = KLD(0, 0), b0 = KLD(0, 1), a1 = KLD(1, 0), b1 = KLD(1, 1), a2, b2;
;     ...
;   QSTEP(0, a0, b0, a2, b2); QSTEP(1, a1, b1, a0, b0); QSTEP(2, a2, b2, a1, b1);
;   QSTEP(3, a0, b0, a2, b2); QSTEP(4, a1, b1, a0, b0); QSTEP(5, a2, b2, a1, b1);
;   QSTEP(6, a0, b0, a2, b2); QSTEP(7, a1, b1, a0, b0); QSTEP(8, a2, b2, a1, b1);
;   QSTEP(9, a0, b0, a2, b2); QSTEP(10, a1, b1, a0, b0); QSTEP(11, a2, b2, a1, b1);
; __device__ __forceinline__ void pv2(f32x16* o, int vb, bf16x8 pa0, bf16x8 pa1, bf16x8 pa2, bf16x8 pa3) {
;   VSet X, Y;
;   SBAR(); v_issue<0>(X, vb); v_issue<1>(Y, vb);
;   asm volatile("s_waitcnt lgkmcnt(8)" ::: "memory"); SBAR(); v_mma(o[0], X, pa0, pa1, pa2, pa3); SBAR();
;   v_issue<2>(X, vb);
;   asm volatile("s_waitcnt lgkmcnt(8)" ::: "memory"); SBAR(); v_mma(o[1], Y, pa0, pa1, pa2, pa3); SBAR();
;   v_issue<3>(Y, vb);
;   asm volatile("s_waitcnt lgkmcnt(8)" ::: "memory"); SBAR(); v_mma(o[2], X, pa0, pa1, pa2, pa3); SBAR();
;   asm volatile("s_waitcnt lgkmcnt(0)" ::: "memory"); SBAR(); v_mma(o[3], Y, pa0, pa1, pa2, pa3); SBAR();
; }
	s_nop 0
	s_nop 0
	v_mfma_f32_32x32x16_bf16 v[0:15], v[64:67], v[80:83], v[0:15]
	v_mfma_f32_32x32x16_bf16 v[0:15], v[68:71], v[84:87], v[0:15]
	v_mfma_f32_32x32x16_bf16 v[0:15], v[72:75], v[88:91], v[0:15]
	v_mfma_f32_32x32x16_bf16 v[0:15], v[76:79], v[92:95], v[0:15]
	ds_read_b64_tr_b16 v[80:81], v206 offset:0x400
	ds_read_b64_tr_b16 v[82:83], v206 offset:0xc00
	ds_read_b64_tr_b16 v[84:85], v206 offset:0x1400
	ds_read_b64_tr_b16 v[86:87], v206 offset:0x1c00
	ds_read_b64_tr_b16 v[88:89], v206 offset:0x2400
	ds_read_b64_tr_b16 v[90:91], v206 offset:0x2c00
	ds_read_b64_tr_b16 v[92:93], v206 offset:0x3400
	ds_read_b64_tr_b16 v[94:95], v206 offset:0x3c00
	s_waitcnt lgkmcnt(8)
	s_nop 0
	v_mfma_f32_32x32x16_bf16 v[48:63], v[64:67], v[186:189], v[48:63]
	v_mfma_f32_32x32x16_bf16 v[48:63], v[68:71], v[190:193], v[48:63]
	v_mfma_f32_32x32x16_bf16 v[48:63], v[72:75], v[194:197], v[48:63]
	v_mfma_f32_32x32x16_bf16 v[48:63], v[76:79], v[214:217], v[48:63]
	ds_read_b64_tr_b16 v[186:187], v206 offset:0x600
	ds_read_b64_tr_b16 v[188:189], v206 offset:0xe00
	ds_read_b64_tr_b16 v[190:191], v206 offset:0x1600
	ds_read_b64_tr_b16 v[192:193], v206 offset:0x1e00
	ds_read_b64_tr_b16 v[194:195], v206 offset:0x2600
	ds_read_b64_tr_b16 v[196:197], v206 offset:0x2e00
	ds_read_b64_tr_b16 v[214:215], v206 offset:0x3600
	ds_read_b64_tr_b16 v[216:217], v206 offset:0x3e00
	s_waitcnt lgkmcnt(8)
	s_nop 0
	v_mfma_f32_32x32x16_bf16 v[32:47], v[64:67], v[80:83], v[32:47]
	v_mfma_f32_32x32x16_bf16 v[32:47], v[68:71], v[84:87], v[32:47]
	v_mfma_f32_32x32x16_bf16 v[32:47], v[72:75], v[88:91], v[32:47]
	v_mfma_f32_32x32x16_bf16 v[32:47], v[76:79], v[92:95], v[32:47]
	s_waitcnt lgkmcnt(0)
	s_nop 0
	v_mfma_f32_32x32x16_bf16 v[16:31], v[64:67], v[186:189], v[16:31]
	v_mfma_f32_32x32x16_bf16 v[16:31], v[68:71], v[190:193], v[16:31]
	v_mfma_f32_32x32x16_bf16 v[16:31], v[72:75], v[194:197], v[16:31]
	v_mfma_f32_32x32x16_bf16 v[16:31], v[76:79], v[214:217], v[16:31]
	s_waitcnt lgkmcnt(0)
	s_barrier
	ds_read_b128 v[64:67], v174 offset:12288
	ds_read_b128 v[186:189], v175 offset:12288
	ds_read_b128 v[190:193], v209 offset:57344
	ds_read_b128 v[194:197], v208 offset:57344
	ds_read_b128 v[68:71], v210 offset:57344
	ds_read_b128 v[214:217], v176 offset:12288
	s_waitcnt lgkmcnt(1)
	v_mfma_f32_32x32x16_bf16 v[80:95], v[68:71], v[96:99], 0
	v_mfma_f32_32x32x16_bf16 v[64:79], v[64:67], v[96:99], 0
	ds_read_b128 v[218:221], v207 offset:57344
	ds_read_b128 v[222:225], v177 offset:12288
	v_mfma_f32_32x32x16_bf16 v[80:95], v[190:193], v[100:103], v[80:95]
	v_mfma_f32_32x32x16_bf16 v[64:79], v[186:189], v[100:103], v[64:79]
	ds_read_b128 v[186:189], v210 offset:57472
	ds_read_b128 v[190:193], v174 offset:12416
	v_mfma_f32_32x32x16_bf16 v[80:95], v[194:197], v[104:107], v[80:95]
	s_waitcnt lgkmcnt(4)
	v_mfma_f32_32x32x16_bf16 v[64:79], v[214:217], v[104:107], v[64:79]
	ds_read_b128 v[194:197], v209 offset:57472
	ds_read_b128 v[214:217], v175 offset:12416
	s_waitcnt lgkmcnt(4)
	v_mfma_f32_32x32x16_bf16 v[80:95], v[218:221], v[108:111], v[80:95]
	v_mfma_f32_32x32x16_bf16 v[64:79], v[222:225], v[108:111], v[64:79]
	ds_read_b128 v[218:221], v208 offset:57472
	ds_read_b128 v[222:225], v176 offset:12416
	s_waitcnt lgkmcnt(4)
	v_mfma_f32_32x32x16_bf16 v[80:95], v[186:189], v[112:115], v[80:95]
	v_mfma_f32_32x32x16_bf16 v[64:79], v[190:193], v[112:115], v[64:79]
	ds_read_b128 v[186:189], v207 offset:57472
	ds_read_b128 v[190:193], v177 offset:12416
	s_waitcnt lgkmcnt(4)
	v_mfma_f32_32x32x16_bf16 v[80:95], v[194:197], v[116:119], v[80:95]
	v_mfma_f32_32x32x16_bf16 v[64:79], v[214:217], v[116:119], v[64:79]
	ds_read_b128 v[194:197], v210 offset:57600
	ds_read_b128 v[214:217], v174 offset:12544
	s_waitcnt lgkmcnt(4)
	v_mfma_f32_32x32x16_bf16 v[80:95], v[218:221], v[120:123], v[80:95]
	v_mfma_f32_32x32x16_bf16 v[64:79], v[222:225], v[120:123], v[64:79]
	ds_read_b128 v[218:221], v209 offset:57600
	ds_read_b128 v[222:225], v175 offset:12544
	s_waitcnt lgkmcnt(4)
	v_mfma_f32_32x32x16_bf16 v[80:95], v[186:189], v[124:127], v[80:95]
	v_mfma_f32_32x32x16_bf16 v[64:79], v[190:193], v[124:127], v[64:79]
	ds_read_b128 v[186:189], v208 offset:57600
	ds_read_b128 v[190:193], v176 offset:12544
	s_waitcnt lgkmcnt(4)
	v_mfma_f32_32x32x16_bf16 v[80:95], v[194:197], v[132:135], v[80:95]
	v_mfma_f32_32x32x16_bf16 v[64:79], v[214:217], v[132:135], v[64:79]
	ds_read_b128 v[194:197], v207 offset:57600
	ds_read_b128 v[214:217], v177 offset:12544
	s_waitcnt lgkmcnt(4)
	v_mfma_f32_32x32x16_bf16 v[80:95], v[218:221], v[140:143], v[80:95]
	v_mfma_f32_32x32x16_bf16 v[64:79], v[222:225], v[140:143], v[64:79]
	s_waitcnt lgkmcnt(2)
	v_mfma_f32_32x32x16_bf16 v[80:95], v[186:189], v[128:131], v[80:95]
	v_mfma_f32_32x32x16_bf16 v[64:79], v[190:193], v[128:131], v[64:79]
	s_waitcnt lgkmcnt(0)
	v_mfma_f32_32x32x16_bf16 v[80:95], v[194:197], v[136:139], v[80:95]
	v_mfma_f32_32x32x16_bf16 v[64:79], v[214:217], v[136:139], v[64:79]
	s_nop 9
	v_max_f32_e32 v182, v81, v81
	v_max_f32_e32 v183, v80, v80
	v_max_f32_e32 v182, v183, v182
	v_max3_f32 v182, v182, v82, v83
	v_max3_f32 v182, v182, v84, v85
	v_max3_f32 v182, v182, v86, v87
	v_max3_f32 v182, v182, v88, v89
	v_max3_f32 v182, v182, v90, v91
	v_max3_f32 v182, v182, v92, v93
	v_max3_f32 v182, v182, v94, v95
	v_max3_f32 v182, v182, v64, v65
	v_max3_f32 v182, v182, v66, v67
	v_max3_f32 v182, v182, v68, v69
	v_max3_f32 v182, v182, v70, v71
	v_max3_f32 v182, v182, v72, v73
	v_max3_f32 v182, v182, v74, v75
	v_max3_f32 v182, v182, v76, v77
	v_max3_f32 v182, v182, v78, v79
	v_mov_b32_e32 v183, v182
	s_nop 1
	v_permlane32_swap_b32_e32 v182, v183
	v_max_f32_e32 v183, v183, v183
	v_max_f32_e32 v182, v182, v182
	s_waitcnt lgkmcnt(0)
	s_barrier
	v_max_f32_e32 v182, v182, v183
	s_waitcnt vmcnt(0)
	v_sub_f32_e32 v183, v182, v178
	v_cmp_ge_f32_e64 s[8:9], s30, v183
	s_cmpk_gt_u32 s19, 0xfd
	ds_write_b128 v212, v[144:147]
	ds_write_b128 v212, v[148:151] offset:1024
	ds_write_b128 v211, v[152:155] offset:32768
	ds_write_b128 v211, v[156:159] offset:32896
	ds_write_b128 v211, v[160:163] offset:33024
	s_cbranch_scc1 .LBB0_465
	v_add_co_u32_e32 v148, vcc, 0x28780000, v170
	s_nop 1
	v_addc_co_u32_e32 v149, vcc, 0, v171, vcc
	v_add_co_u32_e32 v160, vcc, 0x1b360000, v168
	global_load_dwordx4 v[144:147], v[148:149], off offset:256
	s_nop 0
	global_load_dwordx4 v[148:151], v[148:149], off offset:384
	v_addc_co_u32_e32 v161, vcc, 0, v169, vcc
	global_load_dwordx4 v[152:155], v[160:161], off
	global_load_dwordx4 v[156:159], v[160:161], off offset:128
	s_nop 0
	global_load_dwordx4 v[160:163], v[160:161], off offset:256

; #define SLOAD(t) do { const long r0_ = TROW(t); const bf16_t* vp_ = Vh + r0_ * LDV + vgo0; const bf16_t* kp_ = Kh + r0_ * LDKK + kgo0; \
;     vs0 = *reinterpret_cast<const bf16x8*>(vp_); vs1 = *reinterpret_cast<const bf16x8*>(vp_ + 64); \
;     ks0 = *reinterpret_cast<const bf16x8*>(kp_); ks1 = *reinterpret_cast<const bf16x8*>(kp_ + 64); ks2 = *reinterpret_cast<const bf16x8*>(kp_ + 128); } while (0)
; #define SWRITE(b) do { *(bf16x8*)(V_lds + (b) * SHM_V + vst0) = vs0; *(bf16x8*)(V_lds + (b) * SHM_V + vst0 + 1024) = vs1; \
;     *(bf16x8*)(K_lds + (b) * SHM_K + klo0) = ks0; *(bf16x8*)(K_lds + (b) * SHM_K + klo0 + 128) = ks1; *(bf16x8*)(K_lds + (b) * SHM_K + klo0 + 256) = ks2; } while (0)
; #define SWAIT() asm volatile("s_waitcnt vmcnt(0)" ::: "memory")
; #define SLOAD(t) do { const long r0_ = TROW(t); const bf16_t* vp_ = Vh + r0_ * LDV + vgo0; const bf16_t* kp_ = Kh + r0_ * LDKK + kgo0; \
;     vs0 = *reinterpret_cast<const bf16x8*>(vp_); vs1 = *reinterpret_cast<const bf16x8*>(vp_ + 64); \
;     ks0 = *reinterpret_cast<const bf16x8*>(kp_); ks1 = *reinterpret_cast<const bf16x8*>(kp_ + 64); ks2 = *reinterpret_cast<const bf16x8*>(kp_ + 128); } while (0)
; #define SWRITE(b) do { *(bf16x8*)(V_lds + (b) * SHM_V + vst0) = vs0; *(bf16x8*)(V_lds + (b) * SHM_V + vst0 + 1024) = vs1; \
;     *(bf16x8*)(K_lds + (b) * SHM_K + klo0) = ks0; *(bf16x8*)(K_lds + (b) * SHM_K + klo0 + 128) = ks1; *(bf16x8*)(K_lds + (b) * SHM_K + klo0 + 256) = ks2; } while (0)
; #define SWAIT() asm volatile("s_waitcnt vmcnt(0)" ::: "memory")
; #define BARRIER() asm volatile("s_waitcnt lgkmcnt(0)\n\ts_barrier" ::: "memory")
; __device__ __forceinline__ void partialSM(f32x16& p0, f32x16& p1, float& m_reg, float& mn, float& alpha) {
;   constexpr float C = SCALE * 1.4426950408889634f;
;   float pmax = p0[0];
; #pragma unroll
;   for (int r = 1; r < 16; ++r) pmax = fmaxf(pmax, p0[r]);
; #pragma unroll
;   for (int r = 0; r < 16; ++r) pmax = fmaxf(pmax, p1[r]);
; __device__ __forceinline__ void attn_unit2(const bf16_t* __restrict__ Qb, const bf16_t* __restrict__ Kh, const bf16_t* __restrict__ Vh, ...
;     ...
;   f32x16 p0, p1; float mn, al = 1.f; bf16x8 pa0, pa1, pa2, pa3; constexpr int NT = NCHUNK;
;   SLOAD(0); SWAIT(); SWRITE(0); BARRIER();
.Lmask0_a:
	s_mov_b64 vcc, -1
	s_nop 7
	v_cndmask_b32_e32 v180, v76, v201, vcc
	v_cndmask_b32_e32 v181, v77, v201, vcc
	v_cndmask_b32_e32 v76, v90, v201, vcc
	v_cndmask_b32_e32 v77, v91, v201, vcc
	v_max_f32_e32 v90, v65, v65
	v_max_f32_e32 v91, v64, v64
	v_max_f32_e32 v90, v91, v90
	v_max3_f32 v90, v90, v66, v67
	v_max3_f32 v90, v90, v68, v69
	v_cndmask_b32_e32 v186, v72, v201, vcc
	v_cndmask_b32_e32 v187, v73, v201, vcc
	v_max3_f32 v90, v90, v70, v71
	v_cndmask_b32_e32 v182, v74, v201, vcc
	v_cndmask_b32_e32 v183, v75, v201, vcc
	v_max3_f32 v90, v90, v186, v187
	v_max3_f32 v90, v90, v182, v183
	v_cndmask_b32_e32 v78, v78, v201, vcc
	v_cndmask_b32_e32 v79, v79, v201, vcc
	v_max3_f32 v90, v90, v180, v181
	v_cndmask_b32_e32 v80, v80, v201, vcc
	v_cndmask_b32_e32 v81, v81, v201, vcc
	v_max3_f32 v90, v90, v78, v79
	v_cndmask_b32_e32 v82, v82, v201, vcc
	v_cndmask_b32_e32 v83, v83, v201, vcc
	v_max3_f32 v90, v90, v80, v81
	v_cndmask_b32_e32 v84, v84, v201, vcc
	v_cndmask_b32_e32 v85, v85, v201, vcc
	v_max3_f32 v90, v90, v82, v83
	v_cndmask_b32_e32 v86, v86, v201, vcc
	v_cndmask_b32_e32 v87, v87, v201, vcc
	v_max3_f32 v90, v90, v84, v85
	v_cndmask_b32_e32 v88, v88, v201, vcc
	v_cndmask_b32_e32 v89, v89, v201, vcc
	v_max3_f32 v90, v90, v86, v87
	v_max3_f32 v90, v90, v88, v89
	v_cndmask_b32_e32 v74, v92, v201, vcc
	v_cndmask_b32_e32 v75, v93, v201, vcc
	v_max3_f32 v90, v90, v76, v77
	v_cndmask_b32_e32 v73, v94, v201, vcc
	v_cndmask_b32_e32 v72, v95, v201, vcc
	v_max3_f32 v90, v90, v74, v75
	v_max3_f32 v90, v90, v73, v72
	s_branch .Lback0_a
